# SwiGLU GEMM epilogues (P1, P10): scale and +1 as packed f32 ops, 36 instead of 44 VALU per 8 outputs
# speedup vs baseline: 1.0021x; 1.0021x over previous
.LBB0_131:
	s_mov_b32 s92, 0xbfb8aa3b
	s_mov_b32 s93, 0xbfb8aa3b
	s_mov_b32 s94, 1.0
	s_mov_b32 s95, 1.0
	v_pk_mul_f32 v[228:229], v[124:125], s[92:93]
	v_pk_mul_f32 v[230:231], v[126:127], s[92:93]
	v_pk_mul_f32 v[232:233], v[116:117], s[92:93]
	v_pk_mul_f32 v[234:235], v[118:119], s[92:93]
	v_exp_f32_e32 v228, v228
	v_exp_f32_e32 v229, v229
	v_exp_f32_e32 v230, v230
	v_exp_f32_e32 v231, v231
	v_exp_f32_e32 v232, v232
	v_exp_f32_e32 v233, v233
	v_exp_f32_e32 v234, v234
	v_exp_f32_e32 v235, v235
	v_pk_add_f32 v[228:229], v[228:229], s[94:95]
	v_pk_add_f32 v[230:231], v[230:231], s[94:95]
	v_pk_add_f32 v[232:233], v[232:233], s[94:95]
	v_pk_add_f32 v[234:235], v[234:235], s[94:95]
	v_rcp_f32_e32 v228, v228
	v_rcp_f32_e32 v229, v229
	v_rcp_f32_e32 v230, v230
	v_rcp_f32_e32 v231, v231
	v_rcp_f32_e32 v232, v232
	v_rcp_f32_e32 v233, v233
	v_rcp_f32_e32 v234, v234
	v_rcp_f32_e32 v235, v235
	v_pk_mul_f32 v[124:125], v[124:125], v[228:229]
	v_pk_mul_f32 v[126:127], v[126:127], v[230:231]
	v_pk_mul_f32 v[116:117], v[116:117], v[232:233]
	v_pk_mul_f32 v[118:119], v[118:119], v[234:235]
	v_pk_mul_f32 v[124:125], v[124:125], v[120:121]
	v_pk_mul_f32 v[126:127], v[126:127], v[122:123]
	v_pk_mul_f32 v[116:117], v[116:117], v[112:113]
	v_pk_mul_f32 v[118:119], v[118:119], v[114:115]
	v_cvt_pk_bf16_f32 v120, v124, v125
	v_cvt_pk_bf16_f32 v121, v126, v127
	v_cvt_pk_bf16_f32 v122, v116, v117
	v_cvt_pk_bf16_f32 v123, v118, v119
	v_pk_mul_f32 v[228:229], v[108:109], s[92:93]
	v_pk_mul_f32 v[230:231], v[110:111], s[92:93]
	v_pk_mul_f32 v[232:233], v[100:101], s[92:93]
	v_pk_mul_f32 v[234:235], v[102:103], s[92:93]
	v_exp_f32_e32 v228, v228
	v_exp_f32_e32 v229, v229
	v_exp_f32_e32 v230, v230
	v_exp_f32_e32 v231, v231
	v_exp_f32_e32 v232, v232
	v_exp_f32_e32 v233, v233
	v_exp_f32_e32 v234, v234
	v_exp_f32_e32 v235, v235
	v_pk_add_f32 v[228:229], v[228:229], s[94:95]
	v_pk_add_f32 v[230:231], v[230:231], s[94:95]
	v_pk_add_f32 v[232:233], v[232:233], s[94:95]
	v_pk_add_f32 v[234:235], v[234:235], s[94:95]
	v_rcp_f32_e32 v228, v228
	v_rcp_f32_e32 v229, v229
	v_rcp_f32_e32 v230, v230
	v_rcp_f32_e32 v231, v231
	v_rcp_f32_e32 v232, v232
	v_rcp_f32_e32 v233, v233
	v_rcp_f32_e32 v234, v234
	v_rcp_f32_e32 v235, v235
	v_pk_mul_f32 v[108:109], v[108:109], v[228:229]
	v_pk_mul_f32 v[110:111], v[110:111], v[230:231]
	v_pk_mul_f32 v[100:101], v[100:101], v[232:233]
	v_pk_mul_f32 v[102:103], v[102:103], v[234:235]
	v_pk_mul_f32 v[108:109], v[108:109], v[104:105]
	v_pk_mul_f32 v[110:111], v[110:111], v[106:107]
	v_pk_mul_f32 v[100:101], v[100:101], v[96:97]
	v_pk_mul_f32 v[102:103], v[102:103], v[98:99]
	v_cvt_pk_bf16_f32 v104, v108, v109
	v_cvt_pk_bf16_f32 v105, v110, v111
	v_cvt_pk_bf16_f32 v106, v100, v101
	v_cvt_pk_bf16_f32 v107, v102, v103
	v_pk_mul_f32 v[228:229], v[92:93], s[92:93]
	v_pk_mul_f32 v[230:231], v[94:95], s[92:93]
	v_pk_mul_f32 v[232:233], v[84:85], s[92:93]
	v_pk_mul_f32 v[234:235], v[86:87], s[92:93]
	v_exp_f32_e32 v228, v228
	v_exp_f32_e32 v229, v229
	v_exp_f32_e32 v230, v230
	v_exp_f32_e32 v231, v231
	v_exp_f32_e32 v232, v232
	v_exp_f32_e32 v233, v233
	v_exp_f32_e32 v234, v234
	v_exp_f32_e32 v235, v235
	v_pk_add_f32 v[228:229], v[228:229], s[94:95]
	v_pk_add_f32 v[230:231], v[230:231], s[94:95]
	v_pk_add_f32 v[232:233], v[232:233], s[94:95]
	v_pk_add_f32 v[234:235], v[234:235], s[94:95]
	v_rcp_f32_e32 v228, v228
	v_rcp_f32_e32 v229, v229
	v_rcp_f32_e32 v230, v230
	v_rcp_f32_e32 v231, v231
	v_rcp_f32_e32 v232, v232
	v_rcp_f32_e32 v233, v233
	v_rcp_f32_e32 v234, v234
	v_rcp_f32_e32 v235, v235
	v_pk_mul_f32 v[92:93], v[92:93], v[228:229]
	v_pk_mul_f32 v[94:95], v[94:95], v[230:231]
	v_pk_mul_f32 v[84:85], v[84:85], v[232:233]
	v_pk_mul_f32 v[86:87], v[86:87], v[234:235]
	v_pk_mul_f32 v[92:93], v[92:93], v[88:89]
	v_pk_mul_f32 v[94:95], v[94:95], v[90:91]
	v_pk_mul_f32 v[84:85], v[84:85], v[80:81]
	v_pk_mul_f32 v[86:87], v[86:87], v[82:83]
	v_cvt_pk_bf16_f32 v88, v92, v93
	v_cvt_pk_bf16_f32 v89, v94, v95
	v_cvt_pk_bf16_f32 v90, v84, v85
	v_cvt_pk_bf16_f32 v91, v86, v87
	v_pk_mul_f32 v[228:229], v[76:77], s[92:93]
	v_pk_mul_f32 v[230:231], v[78:79], s[92:93]
	v_pk_mul_f32 v[232:233], v[68:69], s[92:93]
	v_pk_mul_f32 v[234:235], v[70:71], s[92:93]
	v_exp_f32_e32 v228, v228
	v_exp_f32_e32 v229, v229
	v_exp_f32_e32 v230, v230
	v_exp_f32_e32 v231, v231
	v_exp_f32_e32 v232, v232
	v_exp_f32_e32 v233, v233
	v_exp_f32_e32 v234, v234
	v_exp_f32_e32 v235, v235
	v_pk_add_f32 v[228:229], v[228:229], s[94:95]
	v_pk_add_f32 v[230:231], v[230:231], s[94:95]
	v_pk_add_f32 v[232:233], v[232:233], s[94:95]
	v_pk_add_f32 v[234:235], v[234:235], s[94:95]
	v_rcp_f32_e32 v228, v228
	v_rcp_f32_e32 v229, v229
	v_rcp_f32_e32 v230, v230
	v_rcp_f32_e32 v231, v231
	v_rcp_f32_e32 v232, v232
	v_rcp_f32_e32 v233, v233
	v_rcp_f32_e32 v234, v234
	v_rcp_f32_e32 v235, v235
	v_pk_mul_f32 v[76:77], v[76:77], v[228:229]
	v_pk_mul_f32 v[78:79], v[78:79], v[230:231]
	v_pk_mul_f32 v[68:69], v[68:69], v[232:233]
	v_pk_mul_f32 v[70:71], v[70:71], v[234:235]
	v_pk_mul_f32 v[76:77], v[76:77], v[72:73]
	v_pk_mul_f32 v[78:79], v[78:79], v[74:75]
	v_pk_mul_f32 v[68:69], v[68:69], v[64:65]
	v_pk_mul_f32 v[70:71], v[70:71], v[66:67]
	v_cvt_pk_bf16_f32 v72, v76, v77
	v_cvt_pk_bf16_f32 v73, v78, v79
	v_cvt_pk_bf16_f32 v74, v68, v69
	v_cvt_pk_bf16_f32 v75, v70, v71
	v_pk_mul_f32 v[228:229], v[60:61], s[92:93]
	v_pk_mul_f32 v[230:231], v[62:63], s[92:93]
	v_pk_mul_f32 v[232:233], v[52:53], s[92:93]
	v_pk_mul_f32 v[234:235], v[54:55], s[92:93]
	v_exp_f32_e32 v228, v228
	v_exp_f32_e32 v229, v229
	v_exp_f32_e32 v230, v230
	v_exp_f32_e32 v231, v231
	v_exp_f32_e32 v232, v232
	v_exp_f32_e32 v233, v233
	v_exp_f32_e32 v234, v234
	v_exp_f32_e32 v235, v235
	v_pk_add_f32 v[228:229], v[228:229], s[94:95]
	v_pk_add_f32 v[230:231], v[230:231], s[94:95]
	v_pk_add_f32 v[232:233], v[232:233], s[94:95]
	v_pk_add_f32 v[234:235], v[234:235], s[94:95]
	v_rcp_f32_e32 v228, v228
	v_rcp_f32_e32 v229, v229
	v_rcp_f32_e32 v230, v230
	v_rcp_f32_e32 v231, v231
	v_rcp_f32_e32 v232, v232
	v_rcp_f32_e32 v233, v233
	v_rcp_f32_e32 v234, v234
	v_rcp_f32_e32 v235, v235
	v_pk_mul_f32 v[60:61], v[60:61], v[228:229]
	v_pk_mul_f32 v[62:63], v[62:63], v[230:231]
	v_pk_mul_f32 v[52:53], v[52:53], v[232:233]
	v_pk_mul_f32 v[54:55], v[54:55], v[234:235]
	v_pk_mul_f32 v[60:61], v[60:61], v[56:57]
	v_pk_mul_f32 v[62:63], v[62:63], v[58:59]
	v_pk_mul_f32 v[52:53], v[52:53], v[48:49]
	v_pk_mul_f32 v[54:55], v[54:55], v[50:51]
	v_cvt_pk_bf16_f32 v56, v60, v61
	v_cvt_pk_bf16_f32 v57, v62, v63
	v_cvt_pk_bf16_f32 v58, v52, v53
	v_cvt_pk_bf16_f32 v59, v54, v55
	v_pk_mul_f32 v[228:229], v[44:45], s[92:93]
	v_pk_mul_f32 v[230:231], v[46:47], s[92:93]
	v_pk_mul_f32 v[232:233], v[36:37], s[92:93]
	v_pk_mul_f32 v[234:235], v[38:39], s[92:93]
	v_exp_f32_e32 v228, v228
	v_exp_f32_e32 v229, v229
	v_exp_f32_e32 v230, v230
	v_exp_f32_e32 v231, v231
	v_exp_f32_e32 v232, v232
	v_exp_f32_e32 v233, v233
	v_exp_f32_e32 v234, v234
	v_exp_f32_e32 v235, v235
	v_pk_add_f32 v[228:229], v[228:229], s[94:95]
	v_pk_add_f32 v[230:231], v[230:231], s[94:95]
	v_pk_add_f32 v[232:233], v[232:233], s[94:95]
	v_pk_add_f32 v[234:235], v[234:235], s[94:95]
	v_rcp_f32_e32 v228, v228
	v_rcp_f32_e32 v229, v229
	v_rcp_f32_e32 v230, v230
	v_rcp_f32_e32 v231, v231
	v_rcp_f32_e32 v232, v232
	v_rcp_f32_e32 v233, v233
	v_rcp_f32_e32 v234, v234
	v_rcp_f32_e32 v235, v235
	v_pk_mul_f32 v[44:45], v[44:45], v[228:229]
	v_pk_mul_f32 v[46:47], v[46:47], v[230:231]
	v_pk_mul_f32 v[36:37], v[36:37], v[232:233]
	v_pk_mul_f32 v[38:39], v[38:39], v[234:235]
	v_pk_mul_f32 v[44:45], v[44:45], v[40:41]
	v_pk_mul_f32 v[46:47], v[46:47], v[42:43]
	v_pk_mul_f32 v[36:37], v[36:37], v[32:33]
	v_pk_mul_f32 v[38:39], v[38:39], v[34:35]
	v_cvt_pk_bf16_f32 v40, v44, v45
	v_cvt_pk_bf16_f32 v41, v46, v47
	v_cvt_pk_bf16_f32 v42, v36, v37
	v_cvt_pk_bf16_f32 v43, v38, v39
	v_pk_mul_f32 v[228:229], v[28:29], s[92:93]
	v_pk_mul_f32 v[230:231], v[30:31], s[92:93]
	v_pk_mul_f32 v[232:233], v[20:21], s[92:93]
	v_pk_mul_f32 v[234:235], v[22:23], s[92:93]
	v_exp_f32_e32 v228, v228
	v_exp_f32_e32 v229, v229
	v_exp_f32_e32 v230, v230
	v_exp_f32_e32 v231, v231
	v_exp_f32_e32 v232, v232
	v_exp_f32_e32 v233, v233
	v_exp_f32_e32 v234, v234
	v_exp_f32_e32 v235, v235
	v_pk_add_f32 v[228:229], v[228:229], s[94:95]
	v_pk_add_f32 v[230:231], v[230:231], s[94:95]
	v_pk_add_f32 v[232:233], v[232:233], s[94:95]
	v_pk_add_f32 v[234:235], v[234:235], s[94:95]
	v_rcp_f32_e32 v228, v228
	v_rcp_f32_e32 v229, v229
	v_rcp_f32_e32 v230, v230
	v_rcp_f32_e32 v231, v231
	v_rcp_f32_e32 v232, v232
	v_rcp_f32_e32 v233, v233
	v_rcp_f32_e32 v234, v234
	v_rcp_f32_e32 v235, v235
	v_pk_mul_f32 v[28:29], v[28:29], v[228:229]
	v_pk_mul_f32 v[30:31], v[30:31], v[230:231]
	v_pk_mul_f32 v[20:21], v[20:21], v[232:233]
	v_pk_mul_f32 v[22:23], v[22:23], v[234:235]
	v_pk_mul_f32 v[28:29], v[28:29], v[24:25]
	v_pk_mul_f32 v[30:31], v[30:31], v[26:27]
	v_pk_mul_f32 v[20:21], v[20:21], v[16:17]
	v_pk_mul_f32 v[22:23], v[22:23], v[18:19]
	v_cvt_pk_bf16_f32 v24, v28, v29
	v_cvt_pk_bf16_f32 v25, v30, v31
	v_cvt_pk_bf16_f32 v26, v20, v21
	v_cvt_pk_bf16_f32 v27, v22, v23
	v_pk_mul_f32 v[228:229], v[12:13], s[92:93]
	v_pk_mul_f32 v[230:231], v[14:15], s[92:93]
	v_pk_mul_f32 v[232:233], v[4:5], s[92:93]
	v_pk_mul_f32 v[234:235], v[6:7], s[92:93]
	v_exp_f32_e32 v228, v228
	v_exp_f32_e32 v229, v229
	v_exp_f32_e32 v230, v230
	v_exp_f32_e32 v231, v231
	v_exp_f32_e32 v232, v232
	v_exp_f32_e32 v233, v233
	v_exp_f32_e32 v234, v234
	v_exp_f32_e32 v235, v235
	v_pk_add_f32 v[228:229], v[228:229], s[94:95]
	v_pk_add_f32 v[230:231], v[230:231], s[94:95]
	v_pk_add_f32 v[232:233], v[232:233], s[94:95]
	v_pk_add_f32 v[234:235], v[234:235], s[94:95]
	v_rcp_f32_e32 v228, v228
	v_rcp_f32_e32 v229, v229
	v_rcp_f32_e32 v230, v230
	v_rcp_f32_e32 v231, v231
	v_rcp_f32_e32 v232, v232
	v_rcp_f32_e32 v233, v233
	v_rcp_f32_e32 v234, v234
	v_rcp_f32_e32 v235, v235
	v_pk_mul_f32 v[12:13], v[12:13], v[228:229]
	v_pk_mul_f32 v[14:15], v[14:15], v[230:231]
	v_pk_mul_f32 v[4:5], v[4:5], v[232:233]
	v_pk_mul_f32 v[6:7], v[6:7], v[234:235]
	v_pk_mul_f32 v[12:13], v[12:13], v[8:9]
	v_pk_mul_f32 v[14:15], v[14:15], v[10:11]
	v_pk_mul_f32 v[4:5], v[4:5], v[0:1]
	v_pk_mul_f32 v[6:7], v[6:7], v[2:3]
	v_cvt_pk_bf16_f32 v8, v12, v13
	v_cvt_pk_bf16_f32 v9, v14, v15
	v_cvt_pk_bf16_f32 v10, v4, v5
	v_cvt_pk_bf16_f32 v11, v6, v7
	v_lshl_add_u32 v154, s28, 8, v148
	v_lshl_or_b32 v144, s49, 7, v150
	v_ashrrev_i32_e32 v145, 31, v144
	v_mov_b64_e32 v[146:147], s[14:15]
	v_or_b32_e32 v112, 16, v154
	v_or_b32_e32 v96, 32, v154
	v_or_b32_e32 v80, 48, v154
	v_add_u32_e32 v64, 0x80, v154
	v_add_u32_e32 v48, 0x90, v154
	v_add_u32_e32 v32, 0xa0, v154
	v_add_u32_e32 v16, 0xb0, v154
	v_mad_i64_i32 v[156:157], s[30:31], v154, s48, v[146:147]
	v_lshlrev_b64 v[144:145], 1, v[144:145]
	v_mad_i64_i32 v[112:113], s[30:31], v112, s48, v[146:147]
	v_mad_i64_i32 v[96:97], s[30:31], v96, s48, v[146:147]
	v_mad_i64_i32 v[80:81], s[30:31], v80, s48, v[146:147]
	v_mad_i64_i32 v[64:65], s[30:31], v64, s48, v[146:147]
	v_mad_i64_i32 v[48:49], s[30:31], v48, s48, v[146:147]
	v_mad_i64_i32 v[32:33], s[30:31], v32, s48, v[146:147]
	v_mad_i64_i32 v[16:17], s[30:31], v16, s48, v[146:147]
	v_lshl_add_u64 v[156:157], v[156:157], 0, v[144:145]
	v_lshl_add_u64 v[112:113], v[112:113], 0, v[144:145]
	v_lshl_add_u64 v[96:97], v[96:97], 0, v[144:145]
	v_lshl_add_u64 v[80:81], v[80:81], 0, v[144:145]
	v_lshl_add_u64 v[64:65], v[64:65], 0, v[144:145]
	v_lshl_add_u64 v[48:49], v[48:49], 0, v[144:145]
	v_lshl_add_u64 v[32:33], v[32:33], 0, v[144:145]
	v_lshl_add_u64 v[16:17], v[16:17], 0, v[144:145]
	s_andn2_b64 vcc, exec, s[6:7]
	s_mov_b64 s[6:7], -1
	global_store_dwordx4 v[156:157], v[120:123], off
	global_store_dwordx4 v[112:113], v[104:107], off
	global_store_dwordx4 v[96:97], v[88:91], off
	global_store_dwordx4 v[80:81], v[72:75], off
	global_store_dwordx4 v[64:65], v[56:59], off
	global_store_dwordx4 v[48:49], v[40:43], off
	global_store_dwordx4 v[32:33], v[24:27], off
	global_store_dwordx4 v[16:17], v[8:11], off
	s_cbranch_vccnz .LBB0_120
	s_andn2_b64 vcc, exec, s[4:5]
	s_cbranch_vccnz .LBB0_119
	s_barrier
	s_branch .LBB0_119

.LBB0_1155:
	s_mov_b32 s92, 0xbfb8aa3b
	s_mov_b32 s93, 0xbfb8aa3b
	s_mov_b32 s94, 1.0
	s_mov_b32 s95, 1.0
	v_pk_mul_f32 v[228:229], v[124:125], s[92:93]
	v_pk_mul_f32 v[230:231], v[126:127], s[92:93]
	v_pk_mul_f32 v[232:233], v[116:117], s[92:93]
	v_pk_mul_f32 v[234:235], v[118:119], s[92:93]
	v_exp_f32_e32 v228, v228
	v_exp_f32_e32 v229, v229
	v_exp_f32_e32 v230, v230
	v_exp_f32_e32 v231, v231
	v_exp_f32_e32 v232, v232
	v_exp_f32_e32 v233, v233
	v_exp_f32_e32 v234, v234
	v_exp_f32_e32 v235, v235
	v_pk_add_f32 v[228:229], v[228:229], s[94:95]
	v_pk_add_f32 v[230:231], v[230:231], s[94:95]
	v_pk_add_f32 v[232:233], v[232:233], s[94:95]
	v_pk_add_f32 v[234:235], v[234:235], s[94:95]
	v_rcp_f32_e32 v228, v228
	v_rcp_f32_e32 v229, v229
	v_rcp_f32_e32 v230, v230
	v_rcp_f32_e32 v231, v231
	v_rcp_f32_e32 v232, v232
	v_rcp_f32_e32 v233, v233
	v_rcp_f32_e32 v234, v234
	v_rcp_f32_e32 v235, v235
	v_pk_mul_f32 v[124:125], v[124:125], v[228:229]
	v_pk_mul_f32 v[126:127], v[126:127], v[230:231]
	v_pk_mul_f32 v[116:117], v[116:117], v[232:233]
	v_pk_mul_f32 v[118:119], v[118:119], v[234:235]
	v_pk_mul_f32 v[124:125], v[124:125], v[120:121]
	v_pk_mul_f32 v[126:127], v[126:127], v[122:123]
	v_pk_mul_f32 v[116:117], v[116:117], v[112:113]
	v_pk_mul_f32 v[118:119], v[118:119], v[114:115]
	v_cvt_pk_bf16_f32 v120, v124, v125
	v_cvt_pk_bf16_f32 v121, v126, v127
	v_cvt_pk_bf16_f32 v122, v116, v117
	v_cvt_pk_bf16_f32 v123, v118, v119
	v_pk_mul_f32 v[228:229], v[108:109], s[92:93]
	v_pk_mul_f32 v[230:231], v[110:111], s[92:93]
	v_pk_mul_f32 v[232:233], v[100:101], s[92:93]
	v_pk_mul_f32 v[234:235], v[102:103], s[92:93]
	v_exp_f32_e32 v228, v228
	v_exp_f32_e32 v229, v229
	v_exp_f32_e32 v230, v230
	v_exp_f32_e32 v231, v231
	v_exp_f32_e32 v232, v232
	v_exp_f32_e32 v233, v233
	v_exp_f32_e32 v234, v234
	v_exp_f32_e32 v235, v235
	v_pk_add_f32 v[228:229], v[228:229], s[94:95]
	v_pk_add_f32 v[230:231], v[230:231], s[94:95]
	v_pk_add_f32 v[232:233], v[232:233], s[94:95]
	v_pk_add_f32 v[234:235], v[234:235], s[94:95]
	v_rcp_f32_e32 v228, v228
	v_rcp_f32_e32 v229, v229
	v_rcp_f32_e32 v230, v230
	v_rcp_f32_e32 v231, v231
	v_rcp_f32_e32 v232, v232
	v_rcp_f32_e32 v233, v233
	v_rcp_f32_e32 v234, v234
	v_rcp_f32_e32 v235, v235
	v_pk_mul_f32 v[108:109], v[108:109], v[228:229]
	v_pk_mul_f32 v[110:111], v[110:111], v[230:231]
	v_pk_mul_f32 v[100:101], v[100:101], v[232:233]
	v_pk_mul_f32 v[102:103], v[102:103], v[234:235]
	v_pk_mul_f32 v[108:109], v[108:109], v[104:105]
	v_pk_mul_f32 v[110:111], v[110:111], v[106:107]
	v_pk_mul_f32 v[100:101], v[100:101], v[96:97]
	v_pk_mul_f32 v[102:103], v[102:103], v[98:99]
	v_cvt_pk_bf16_f32 v104, v108, v109
	v_cvt_pk_bf16_f32 v105, v110, v111
	v_cvt_pk_bf16_f32 v106, v100, v101
	v_cvt_pk_bf16_f32 v107, v102, v103
	v_pk_mul_f32 v[228:229], v[92:93], s[92:93]
	v_pk_mul_f32 v[230:231], v[94:95], s[92:93]
	v_pk_mul_f32 v[232:233], v[84:85], s[92:93]
	v_pk_mul_f32 v[234:235], v[86:87], s[92:93]
	v_exp_f32_e32 v228, v228
	v_exp_f32_e32 v229, v229
	v_exp_f32_e32 v230, v230
	v_exp_f32_e32 v231, v231
	v_exp_f32_e32 v232, v232
	v_exp_f32_e32 v233, v233
	v_exp_f32_e32 v234, v234
	v_exp_f32_e32 v235, v235
	v_pk_add_f32 v[228:229], v[228:229], s[94:95]
	v_pk_add_f32 v[230:231], v[230:231], s[94:95]
	v_pk_add_f32 v[232:233], v[232:233], s[94:95]
	v_pk_add_f32 v[234:235], v[234:235], s[94:95]
	v_rcp_f32_e32 v228, v228
	v_rcp_f32_e32 v229, v229
	v_rcp_f32_e32 v230, v230
	v_rcp_f32_e32 v231, v231
	v_rcp_f32_e32 v232, v232
	v_rcp_f32_e32 v233, v233
	v_rcp_f32_e32 v234, v234
	v_rcp_f32_e32 v235, v235
	v_pk_mul_f32 v[92:93], v[92:93], v[228:229]
	v_pk_mul_f32 v[94:95], v[94:95], v[230:231]
	v_pk_mul_f32 v[84:85], v[84:85], v[232:233]
	v_pk_mul_f32 v[86:87], v[86:87], v[234:235]
	v_pk_mul_f32 v[92:93], v[92:93], v[88:89]
	v_pk_mul_f32 v[94:95], v[94:95], v[90:91]
	v_pk_mul_f32 v[84:85], v[84:85], v[80:81]
	v_pk_mul_f32 v[86:87], v[86:87], v[82:83]
	v_cvt_pk_bf16_f32 v88, v92, v93
	v_cvt_pk_bf16_f32 v89, v94, v95
	v_cvt_pk_bf16_f32 v90, v84, v85
	v_cvt_pk_bf16_f32 v91, v86, v87
	v_pk_mul_f32 v[228:229], v[76:77], s[92:93]
	v_pk_mul_f32 v[230:231], v[78:79], s[92:93]
	v_pk_mul_f32 v[232:233], v[68:69], s[92:93]
	v_pk_mul_f32 v[234:235], v[70:71], s[92:93]
	v_exp_f32_e32 v228, v228
	v_exp_f32_e32 v229, v229
	v_exp_f32_e32 v230, v230
	v_exp_f32_e32 v231, v231
	v_exp_f32_e32 v232, v232
	v_exp_f32_e32 v233, v233
	v_exp_f32_e32 v234, v234
	v_exp_f32_e32 v235, v235
	v_pk_add_f32 v[228:229], v[228:229], s[94:95]
	v_pk_add_f32 v[230:231], v[230:231], s[94:95]
	v_pk_add_f32 v[232:233], v[232:233], s[94:95]
	v_pk_add_f32 v[234:235], v[234:235], s[94:95]
	v_rcp_f32_e32 v228, v228
	v_rcp_f32_e32 v229, v229
	v_rcp_f32_e32 v230, v230
	v_rcp_f32_e32 v231, v231
	v_rcp_f32_e32 v232, v232
	v_rcp_f32_e32 v233, v233
	v_rcp_f32_e32 v234, v234
	v_rcp_f32_e32 v235, v235
	v_pk_mul_f32 v[76:77], v[76:77], v[228:229]
	v_pk_mul_f32 v[78:79], v[78:79], v[230:231]
	v_pk_mul_f32 v[68:69], v[68:69], v[232:233]
	v_pk_mul_f32 v[70:71], v[70:71], v[234:235]
	v_pk_mul_f32 v[76:77], v[76:77], v[72:73]
	v_pk_mul_f32 v[78:79], v[78:79], v[74:75]
	v_pk_mul_f32 v[68:69], v[68:69], v[64:65]
	v_pk_mul_f32 v[70:71], v[70:71], v[66:67]
	v_cvt_pk_bf16_f32 v72, v76, v77
	v_cvt_pk_bf16_f32 v73, v78, v79
	v_cvt_pk_bf16_f32 v74, v68, v69
	v_cvt_pk_bf16_f32 v75, v70, v71
	v_pk_mul_f32 v[228:229], v[60:61], s[92:93]
	v_pk_mul_f32 v[230:231], v[62:63], s[92:93]
	v_pk_mul_f32 v[232:233], v[52:53], s[92:93]
	v_pk_mul_f32 v[234:235], v[54:55], s[92:93]
	v_exp_f32_e32 v228, v228
	v_exp_f32_e32 v229, v229
	v_exp_f32_e32 v230, v230
	v_exp_f32_e32 v231, v231
	v_exp_f32_e32 v232, v232
	v_exp_f32_e32 v233, v233
	v_exp_f32_e32 v234, v234
	v_exp_f32_e32 v235, v235
	v_pk_add_f32 v[228:229], v[228:229], s[94:95]
	v_pk_add_f32 v[230:231], v[230:231], s[94:95]
	v_pk_add_f32 v[232:233], v[232:233], s[94:95]
	v_pk_add_f32 v[234:235], v[234:235], s[94:95]
	v_rcp_f32_e32 v228, v228
	v_rcp_f32_e32 v229, v229
	v_rcp_f32_e32 v230, v230
	v_rcp_f32_e32 v231, v231
	v_rcp_f32_e32 v232, v232
	v_rcp_f32_e32 v233, v233
	v_rcp_f32_e32 v234, v234
	v_rcp_f32_e32 v235, v235
	v_pk_mul_f32 v[60:61], v[60:61], v[228:229]
	v_pk_mul_f32 v[62:63], v[62:63], v[230:231]
	v_pk_mul_f32 v[52:53], v[52:53], v[232:233]
	v_pk_mul_f32 v[54:55], v[54:55], v[234:235]
	v_pk_mul_f32 v[60:61], v[60:61], v[56:57]
	v_pk_mul_f32 v[62:63], v[62:63], v[58:59]
	v_pk_mul_f32 v[52:53], v[52:53], v[48:49]
	v_pk_mul_f32 v[54:55], v[54:55], v[50:51]
	v_cvt_pk_bf16_f32 v56, v60, v61
	v_cvt_pk_bf16_f32 v57, v62, v63
	v_cvt_pk_bf16_f32 v58, v52, v53
	v_cvt_pk_bf16_f32 v59, v54, v55
	v_pk_mul_f32 v[228:229], v[44:45], s[92:93]
	v_pk_mul_f32 v[230:231], v[46:47], s[92:93]
	v_pk_mul_f32 v[232:233], v[36:37], s[92:93]
	v_pk_mul_f32 v[234:235], v[38:39], s[92:93]
	v_exp_f32_e32 v228, v228
	v_exp_f32_e32 v229, v229
	v_exp_f32_e32 v230, v230
	v_exp_f32_e32 v231, v231
	v_exp_f32_e32 v232, v232
	v_exp_f32_e32 v233, v233
	v_exp_f32_e32 v234, v234
	v_exp_f32_e32 v235, v235
	v_pk_add_f32 v[228:229], v[228:229], s[94:95]
	v_pk_add_f32 v[230:231], v[230:231], s[94:95]
	v_pk_add_f32 v[232:233], v[232:233], s[94:95]
	v_pk_add_f32 v[234:235], v[234:235], s[94:95]
	v_rcp_f32_e32 v228, v228
	v_rcp_f32_e32 v229, v229
	v_rcp_f32_e32 v230, v230
	v_rcp_f32_e32 v231, v231
	v_rcp_f32_e32 v232, v232
	v_rcp_f32_e32 v233, v233
	v_rcp_f32_e32 v234, v234
	v_rcp_f32_e32 v235, v235
	v_pk_mul_f32 v[44:45], v[44:45], v[228:229]
	v_pk_mul_f32 v[46:47], v[46:47], v[230:231]
	v_pk_mul_f32 v[36:37], v[36:37], v[232:233]
	v_pk_mul_f32 v[38:39], v[38:39], v[234:235]
	v_pk_mul_f32 v[44:45], v[44:45], v[40:41]
	v_pk_mul_f32 v[46:47], v[46:47], v[42:43]
	v_pk_mul_f32 v[36:37], v[36:37], v[32:33]
	v_pk_mul_f32 v[38:39], v[38:39], v[34:35]
	v_cvt_pk_bf16_f32 v40, v44, v45
	v_cvt_pk_bf16_f32 v41, v46, v47
	v_cvt_pk_bf16_f32 v42, v36, v37
	v_cvt_pk_bf16_f32 v43, v38, v39
	v_pk_mul_f32 v[228:229], v[28:29], s[92:93]
	v_pk_mul_f32 v[230:231], v[30:31], s[92:93]
	v_pk_mul_f32 v[232:233], v[20:21], s[92:93]
	v_pk_mul_f32 v[234:235], v[22:23], s[92:93]
	v_exp_f32_e32 v228, v228
	v_exp_f32_e32 v229, v229
	v_exp_f32_e32 v230, v230
	v_exp_f32_e32 v231, v231
	v_exp_f32_e32 v232, v232
	v_exp_f32_e32 v233, v233
	v_exp_f32_e32 v234, v234
	v_exp_f32_e32 v235, v235
	v_pk_add_f32 v[228:229], v[228:229], s[94:95]
	v_pk_add_f32 v[230:231], v[230:231], s[94:95]
	v_pk_add_f32 v[232:233], v[232:233], s[94:95]
	v_pk_add_f32 v[234:235], v[234:235], s[94:95]
	v_rcp_f32_e32 v228, v228
	v_rcp_f32_e32 v229, v229
	v_rcp_f32_e32 v230, v230
	v_rcp_f32_e32 v231, v231
	v_rcp_f32_e32 v232, v232
	v_rcp_f32_e32 v233, v233
	v_rcp_f32_e32 v234, v234
	v_rcp_f32_e32 v235, v235
	v_pk_mul_f32 v[28:29], v[28:29], v[228:229]
	v_pk_mul_f32 v[30:31], v[30:31], v[230:231]
	v_pk_mul_f32 v[20:21], v[20:21], v[232:233]
	v_pk_mul_f32 v[22:23], v[22:23], v[234:235]
	v_pk_mul_f32 v[28:29], v[28:29], v[24:25]
	v_pk_mul_f32 v[30:31], v[30:31], v[26:27]
	v_pk_mul_f32 v[20:21], v[20:21], v[16:17]
	v_pk_mul_f32 v[22:23], v[22:23], v[18:19]
	v_cvt_pk_bf16_f32 v24, v28, v29
	v_cvt_pk_bf16_f32 v25, v30, v31
	v_cvt_pk_bf16_f32 v26, v20, v21
	v_cvt_pk_bf16_f32 v27, v22, v23
	v_pk_mul_f32 v[228:229], v[12:13], s[92:93]
	v_pk_mul_f32 v[230:231], v[14:15], s[92:93]
	v_pk_mul_f32 v[232:233], v[4:5], s[92:93]
	v_pk_mul_f32 v[234:235], v[6:7], s[92:93]
	v_exp_f32_e32 v228, v228
	v_exp_f32_e32 v229, v229
	v_exp_f32_e32 v230, v230
	v_exp_f32_e32 v231, v231
	v_exp_f32_e32 v232, v232
	v_exp_f32_e32 v233, v233
	v_exp_f32_e32 v234, v234
	v_exp_f32_e32 v235, v235
	v_pk_add_f32 v[228:229], v[228:229], s[94:95]
	v_pk_add_f32 v[230:231], v[230:231], s[94:95]
	v_pk_add_f32 v[232:233], v[232:233], s[94:95]
	v_pk_add_f32 v[234:235], v[234:235], s[94:95]
	v_rcp_f32_e32 v228, v228
	v_rcp_f32_e32 v229, v229
	v_rcp_f32_e32 v230, v230
	v_rcp_f32_e32 v231, v231
	v_rcp_f32_e32 v232, v232
	v_rcp_f32_e32 v233, v233
	v_rcp_f32_e32 v234, v234
	v_rcp_f32_e32 v235, v235
	v_pk_mul_f32 v[12:13], v[12:13], v[228:229]
	v_pk_mul_f32 v[14:15], v[14:15], v[230:231]
	v_pk_mul_f32 v[4:5], v[4:5], v[232:233]
	v_pk_mul_f32 v[6:7], v[6:7], v[234:235]
	v_pk_mul_f32 v[12:13], v[12:13], v[8:9]
	v_pk_mul_f32 v[14:15], v[14:15], v[10:11]
	v_pk_mul_f32 v[4:5], v[4:5], v[0:1]
	v_pk_mul_f32 v[6:7], v[6:7], v[2:3]
	v_cvt_pk_bf16_f32 v8, v12, v13
	v_cvt_pk_bf16_f32 v9, v14, v15
	v_cvt_pk_bf16_f32 v10, v4, v5
	v_cvt_pk_bf16_f32 v11, v6, v7
	v_lshl_add_u32 v154, s22, 8, v148
	v_lshl_or_b32 v144, s43, 7, v150
	v_ashrrev_i32_e32 v145, 31, v144
	v_mov_b64_e32 v[146:147], s[8:9]
	v_or_b32_e32 v112, 16, v154
	v_or_b32_e32 v96, 32, v154
	v_or_b32_e32 v80, 48, v154
	v_add_u32_e32 v64, 0x80, v154
	v_add_u32_e32 v48, 0x90, v154
	v_add_u32_e32 v32, 0xa0, v154
	v_add_u32_e32 v16, 0xb0, v154
	v_mad_i64_i32 v[156:157], s[24:25], v154, s42, v[146:147]
	v_lshlrev_b64 v[144:145], 1, v[144:145]
	v_mad_i64_i32 v[112:113], s[24:25], v112, s42, v[146:147]
	v_mad_i64_i32 v[96:97], s[24:25], v96, s42, v[146:147]
	v_mad_i64_i32 v[80:81], s[24:25], v80, s42, v[146:147]
	v_mad_i64_i32 v[64:65], s[24:25], v64, s42, v[146:147]
	v_mad_i64_i32 v[48:49], s[24:25], v48, s42, v[146:147]
	v_mad_i64_i32 v[32:33], s[24:25], v32, s42, v[146:147]
	v_mad_i64_i32 v[16:17], s[24:25], v16, s42, v[146:147]
	v_lshl_add_u64 v[156:157], v[156:157], 0, v[144:145]
	v_lshl_add_u64 v[112:113], v[112:113], 0, v[144:145]
	v_lshl_add_u64 v[96:97], v[96:97], 0, v[144:145]
	v_lshl_add_u64 v[80:81], v[80:81], 0, v[144:145]
	v_lshl_add_u64 v[64:65], v[64:65], 0, v[144:145]
	v_lshl_add_u64 v[48:49], v[48:49], 0, v[144:145]
	v_lshl_add_u64 v[32:33], v[32:33], 0, v[144:145]
	v_lshl_add_u64 v[16:17], v[16:17], 0, v[144:145]
	s_andn2_b64 vcc, exec, s[6:7]
	s_mov_b64 s[6:7], -1
	global_store_dwordx4 v[156:157], v[120:123], off
	global_store_dwordx4 v[112:113], v[104:107], off
	global_store_dwordx4 v[96:97], v[88:91], off
	global_store_dwordx4 v[80:81], v[72:75], off
	global_store_dwordx4 v[64:65], v[56:59], off
	global_store_dwordx4 v[48:49], v[40:43], off
	global_store_dwordx4 v[32:33], v[24:27], off
	global_store_dwordx4 v[16:17], v[8:11], off
	s_cbranch_vccnz .LBB0_1144
	s_andn2_b64 vcc, exec, s[4:5]
	s_cbranch_vccnz .LBB0_1143
	s_barrier
	s_branch .LBB0_1143
